# P6 out-proj GEMM: odd row-slot workgroups start ~10us late so the MFMA-bound K loops of one half overlap the HBM-bound f32 epilogues of the other half
# baseline (speedup 1.0000x reference)
; template <class Epi>
; DI void gemm_tile256(const u16* __restrict__ Ag, long lda, const u16* __restrict__ Bg, long ldb, int nk, char* shm, Epi&& epi) {
;   const int tid = RTID, wid = tid >> 6, lane = tid & 63, wr = wid >> 2, wc = wid & 3, fr = lane & 15, fq = lane >> 4;
;   f32x4 acc[8][4];
; #pragma unroll
;   for (int m = 0; m < 8; ++m)
; #pragma unroll
;     for (int n = 0; n < 4; ++n) acc[m][n] = f32x4{0.f, 0.f, 0.f, 0.f};
;   const int q0 = tid, q1 = 512 + tid;
;   const int r0 = q0 >> 2, r1 = q1 >> 2, c0 = (q0 & 3) ^ ((r0 >> 2) & 3), c1 = (q1 & 3) ^ ((r1 >> 2) & 3);
;   const u16* a0 = Ag + (long)r0 * lda + c0 * 8; const u16* a1 = Ag + (long)r1 * lda + c1 * 8;
;   const u16* b0 = Bg + (long)r0 * ldb + c0 * 8; const u16* b1 = Bg + (long)r1 * ldb + c1 * 8;
;   auto stage = [&](int j) {
;     char* SA = shm + (j & 3) * 32768; char* SB = SA + 16384;
;     __builtin_amdgcn_global_load_lds((const unsigned*)(a0 + j * 32), (__attribute__((address_space(3))) unsigned*)(SA + q0 * 16), 16, 0, 0);
;     __builtin_amdgcn_global_load_lds((const unsigned*)(a1 + j * 32), (__attribute__((address_space(3))) unsigned*)(SA + q1 * 16), 16, 0, 0);
;     __builtin_amdgcn_global_load_lds((const unsigned*)(b0 + j * 32), (__attribute__((address_space(3))) unsigned*)(SB + q0 * 16), 16, 0, 0);
;     __builtin_amdgcn_global_load_lds((const unsigned*)(b1 + j * 32), (__attribute__((address_space(3))) unsigned*)(SB + q1 * 16), 16, 0, 0);
;   };
;   __syncthreads();
;   stage(0);
;   if (nk > 1) stage(1);
;   if (nk > 2) stage(2);
; DI void phase6(const Params& P, char* smem) {
;     ...
;   for (int q = RBLK >> 3; q < 64; q += RGRID >> 3) {
;     const int brow = (q * 2 + ((RBLK & 7) >> 2)) * 256, bcol = (RBLK & 3) * 256;
;     gemm_tile256(cat + (long)brow * 1024, 1024, WoT + (long)bcol * 1024, 1024, 32, smem, [&](int row, int col0, f32x4 v) {
;       const long o = (long)(brow + row) * 1024 + bcol + col0;
;       const float4 xs = *reinterpret_cast<const float4*>(P.x + o);
;       *reinterpret_cast<float4*>(Z1 + o) = make_float4(ALPHA * xs.x + v[0], ALPHA * xs.y + v[1], ALPHA * xs.z + v[2], ALPHA * xs.w + v[3]);
;     });
;   }
.LBB0_944:
	s_or_b64 exec, exec, s[0:1]
	s_add_u32 s38, s78, 0x8000000
	s_addc_u32 s39, s79, 0
	s_cmp_gt_i32 s75, 63
	s_waitcnt lgkmcnt(0)
	s_barrier
	s_cbranch_scc1 .LBB0_949
	s_bitcmp1_b32 s75, 0
	s_cbranch_scc0 .Lp6_nostagger
	s_sleep 127
	s_sleep 127
	s_sleep 127
.Lp6_nostagger:
	s_lshl_b32 s0, s74, 6
	s_and_b32 s2, s0, 0x100
	s_lshl_b32 s0, s74, 8
	s_and_b32 s4, s0, 0x300
	s_lshl_b32 s0, s4, 11
	s_add_u32 s0, s78, s0
	s_addc_u32 s1, s79, 0
	v_xor_b32_e32 v0, v193, v189
	s_add_u32 s0, s0, 0x18800000
	v_add_u32_e32 v1, 0x200, v189
	v_mov_b32_e32 v133, 0
	v_lshlrev_b32_e32 v0, 3, v0
	s_addc_u32 s1, s1, 0
	v_lshlrev_b32_e32 v130, 11, v195
	v_mov_b32_e32 v131, v133
	v_and_b32_e32 v0, 24, v0
	v_lshlrev_b32_e32 v2, 9, v1
	v_and_b32_e32 v134, 0xff800, v2
	v_mov_b32_e32 v135, v133
	v_lshl_add_u64 v[2:3], s[0:1], 0, v[130:131]
	v_lshlrev_b32_e32 v132, 1, v0
	v_lshlrev_b32_e32 v149, 4, v1
	v_xor_b32_e32 v1, v193, v195
	v_lshl_add_u64 v[136:137], v[2:3], 0, v[132:133]
	v_lshl_add_u64 v[2:3], s[0:1], 0, v[134:135]
	v_lshlrev_b32_e32 v1, 4, v1
	v_lshl_add_u64 v[138:139], v[2:3], 0, v[132:133]
	v_and_b32_e32 v1, 48, v1
	v_lshlrev_b32_e32 v2, 6, v188
	s_add_i32 s5, 0, 0x18000
	v_lshl_or_b32 v151, v194, 12, v2
	v_lshl_or_b32 v153, v190, 13, v2
	v_add_u32_e32 v6, s5, v1
	s_add_i32 s5, 0, 0x1c000
	v_and_b32_e32 v2, 12, v195
	s_add_i32 s7, 0, 0x10000
	s_add_i32 s8, 0, 0x14000
	v_add_u32_e32 v7, s5, v1
	v_or3_b32 v148, v196, v2, s4
	v_add_u32_e32 v8, s7, v1
	v_add_u32_e32 v9, s8, v1
	v_readlane_b32 s4, v254, 8
	v_add_u32_e32 v183, 0, v1
	v_bitop3_b32 v1, v193, 3, v189 bitop3:0x48
	v_readlane_b32 s5, v254, 9
	v_lshlrev_b32_e32 v1, 4, v1
	s_ashr_i32 s9, s4, 3
	v_or_b32_e32 v132, v130, v1
	s_lshl_b32 s4, s75, 9
	s_lshl_b32 s5, s74, 19
	v_lshl_add_u64 v[2:3], s[78:79], 0, v[132:133]
	s_mov_b64 s[10:11], 0x190000c0
	s_or_b32 s4, s4, s2
	s_lshl_b32 s14, s9, 9
	s_and_b32 s5, s5, 0x180000
	v_lshl_add_u64 v[156:157], v[2:3], 0, s[10:11]
	v_or_b32_e32 v2, v134, v1
	v_mov_b32_e32 v3, v133
	s_add_u32 s12, s78, s5
	v_lshl_add_u64 v[4:5], s[78:79], 0, v[2:3]
	v_or_b32_e32 v132, s5, v132
	s_addc_u32 s13, s79, 0
	s_mov_b64 s[0:1], 0x80
	v_lshl_or_b32 v155, v190, 7, v188
	v_lshl_add_u64 v[158:159], v[4:5], 0, s[10:11]
	v_lshl_add_u64 v[4:5], s[78:79], 0, v[132:133]
	s_mov_b64 s[10:11], 0x188000c0
	v_lshl_add_u64 v[2:3], s[12:13], 0, v[2:3]
	v_lshl_add_u64 v[140:141], v[136:137], 0, 64
	v_lshl_add_u64 v[142:143], v[138:139], 0, 64
	v_lshl_add_u64 v[144:145], v[136:137], 0, s[0:1]
	v_lshl_add_u64 v[146:147], v[138:139], 0, s[0:1]
	v_or_b32_e32 v150, 16, v148
	v_or_b32_e32 v152, 32, v148
	v_or_b32_e32 v154, 48, v148
	v_or_b32_e32 v176, 16, v155
	v_or_b32_e32 v177, 32, v155
	v_or_b32_e32 v178, 48, v155
	v_or_b32_e32 v179, 64, v155
	v_or_b32_e32 v180, 0x50, v155
	v_or_b32_e32 v181, 0x60, v155
	v_or_b32_e32 v182, 0x70, v155
	v_lshl_add_u64 v[160:161], v[4:5], 0, s[10:11]
	v_lshl_add_u64 v[162:163], v[2:3], 0, s[10:11]
	v_lshlrev_b32_e32 v132, 1, v0
	v_add_u32_e32 v184, v8, v153
	v_add_u32_e32 v185, v9, v151
	v_add_u32_e32 v186, v6, v153
	v_add_u32_e32 v187, v7, v151
	s_mov_b32 s6, 0x3f9837f0
	s_mov_b32 s15, s75
